# sel-loop: K-fragment LDS reads hoisted to loop top, staging ds_write moved before PV MFMAs
# speedup vs baseline: 1.0029x; 1.0029x over previous
; #define LAS __attribute__((address_space(3)))
; DI void lds_k(KFrag& K, const LAS unsigned char* buf, int sub, int r32, int hi) {
;     const LAS unsigned char* p = buf + (32 * sub + r32) * 144 + 16 * hi;
; #pragma unroll
;     for (int d0 = 0; d0 < 4; ++d0) K.k[d0] = *(const LAS bf16x8*)(p + 32 * d0);
; }
; DI void nsa_unit(const bf16* PR, const bf16* VT, const bf16* kcb, const bf16* vctb, bf16* Y, LAS unsigned char* lds, int b, int g, int jt) {
;     ...
;         while (jcur >= 0) {
;             int jnext; SEL_NEXT(jnext);
;             if (jnext >= 0) stage_load(R, ks + (size_t)jnext * 64 * 64, 64, vst + 64 * jnext, SEQ, tid, true);
;             const LAS unsigned char* buf = tb + par * TBUF;
;             const int jw = jcur >> 5, jb = jcur & 31;
;             const unsigned wuw = jw == 0 ? wu0 : (jw == 1 ? wu1 : (jw == 2 ? wu2 : wu3));
;             if ((wuw >> jb) & 1u) {
.LBB0_992:
	s_mul_i32 s54, s2, 0x4600
	v_add3_u32 v178, s54, v245, v206
	ds_read_b128 v[2:5], v178
	ds_read_b128 v[6:9], v178 offset:32
	ds_read_b128 v[10:13], v178 offset:4608
	ds_read_b128 v[124:127], v178 offset:4640
	s_cmp_eq_u32 s0, 0
	s_cselect_b64 s[6:7], -1, 0
	s_cmp_gt_i32 s1, 0
	s_cselect_b64 s[8:9], -1, 0
	s_and_b64 s[8:9], s[6:7], s[8:9]
	s_andn2_b64 vcc, exec, s[8:9]
	s_cbranch_vccnz .LBB0_994

; DI void nsa_unit(const bf16* PR, const bf16* VT, const bf16* kcb, const bf16* vctb, bf16* Y, LAS unsigned char* lds, int b, int g, int jt) {
;     ...
;         int jcur; SEL_NEXT(jcur);
;         stage_load(R, ks + (size_t)jcur * 64 * 64, 64, vst + 64 * jcur, SEQ, tid, true); stage_store(tb, R, tid, true); __syncthreads();
;         int par = 0;
;         while (jcur >= 0) {
;             int jnext; SEL_NEXT(jnext);
;             if (jnext >= 0) stage_load(R, ks + (size_t)jnext * 64 * 64, 64, vst + 64 * jnext, SEQ, tid, true);
.LBB0_994:
	s_flbit_i32_b32 s3, s0
	s_xor_b32 s53, s3, 31
	s_lshl_b32 s3, s1, 5
	s_or_b32 s3, s53, s3
	s_and_b64 s[6:7], s[6:7], exec
	s_cselect_b32 s94, -1, s3
	s_cmp_gt_i32 s94, -1
	s_cselect_b64 s[42:43], -1, 0
	s_cmp_lt_i32 s94, 0
	s_cselect_b64 s[40:41], -1, 0
	s_and_b64 vcc, exec, s[40:41]
	s_cbranch_vccnz .LBB0_996
	s_lshl_b64 s[6:7], s[94:95], 13
	s_lshl_b32 s94, s94, 6
	v_lshl_add_u64 v[180:181], v[160:161], 0, s[6:7]
	v_lshl_add_u64 v[182:183], s[94:95], 1, v[162:163]
	global_load_dwordx4 v[116:119], v[180:181], off
	global_load_dwordx4 v[120:123], v[182:183], off
; #define LAS __attribute__((address_space(3)))
; #define MFMA32(a, b, c) __builtin_amdgcn_mfma_f32_32x32x16_bf16((a), (b), (c), 0, 0, 0)
; DI int crow(int r, int hi) { return (r & 3) + 8 * (r >> 2) + 4 * hi; }
; DI int ccol(int r) { return (r & 3) + 8 * (r >> 2); }
; DI void lds_v(VFrag& V, const LAS unsigned char* buf, int sub, int r32, int hi) {
; #pragma unroll
;     for (int s = 0; s < 2; ++s)
; #pragma unroll
;         for (int d0 = 0; d0 < 2; ++d0) {
;             const LAS unsigned char* p = buf + KB_BYTES + (r32 + 32 * d0) * 136 + (32 * sub + 16 * s + 4 * hi) * 2;
;             V.v[(2 * s + d0) * 2] = *(const LAS u32x2*)p; V.v[(2 * s + d0) * 2 + 1] = *(const LAS u32x2*)(p + 16);
;         }
; }
; DI void tile_scores(f32x16& x0, f32x16& x1, const LAS unsigned char* buf, const bf16x8 (&qf)[4], float sk, float aref, int p0, bool laneok, bool needmask, int lo, int hip, int r32, int hi) {
;     KFrag K0, K1; lds_k(K0, buf, 0, r32, hi); lds_k(K1, buf, 1, r32, hi);
;     const float B = laneok ? fmaf(sk, (float)(p0 + 4 * hi), -aref) : -1e30f;
;     const float B1 = B + 32.f * sk;
; #pragma unroll
;     for (int r = 0; r < 16; ++r) { x0[r] = fmaf(sk, (float)ccol(r), B); x1[r] = fmaf(sk, (float)ccol(r), B1); }
; #pragma unroll
;     for (int d0 = 0; d0 < 4; ++d0) { x0 = MFMA32(K0.k[d0], qf[d0], x0); x1 = MFMA32(K1.k[d0], qf[d0], x1); }
;     if (needmask) {
; #pragma unroll
;         for (int r = 0; r < 16; ++r) { const int pos = p0 + crow(r, hi); if (pos < lo || pos > hip) x0[r] = -1e30f; if (pos + 32 < lo || pos + 32 > hip) x1[r] = -1e30f; }
;     }
; }
.LBB0_996:
	s_lshr_b32 s8, s10, 5
	s_cmp_eq_u32 s8, 2
	s_cselect_b64 vcc, -1, 0
	s_and_b64 s[6:7], vcc, exec
	s_cselect_b32 s11, s50, s52
	s_cmp_eq_u32 s8, 1
	s_cselect_b64 s[6:7], -1, 0
	s_and_b64 s[8:9], s[6:7], exec
	s_cselect_b32 s11, s48, s11
	s_cmp_lt_u32 s10, 32
	s_cselect_b64 s[8:9], -1, 0
	s_and_b64 s[12:13], s[8:9], exec
	s_cselect_b32 s12, s46, s11
	s_lshl_b32 s11, 1, s10
	s_and_b32 s12, s12, s11
	s_cmp_eq_u32 s12, 0
	s_cbranch_scc1 .LBB0_1008
	v_cndmask_b32_e32 v1, v115, v114, vcc
	v_cndmask_b32_e64 v1, v1, v113, s[6:7]
	v_cndmask_b32_e64 v1, v1, v112, s[8:9]
	v_and_b32_e32 v14, s11, v1
	v_lshl_or_b32 v1, s10, 6, v240
	v_cvt_f32_u32_e32 v80, v1
	s_mul_i32 s12, s2, 0x4600
	s_add_i32 s12, s12, 0
	v_add_f32_e32 v15, v247, v167
	v_add3_u32 v128, s12, v245, v206
	v_fma_f32 v15, v208, v80, -v15
	v_cmp_ne_u32_e32 vcc, 0, v14
	s_nop 1
	v_cndmask_b32_e32 v14, v222, v15, vcc
	v_fma_f32 v96, 0, v208, v14
	v_add_f32_e32 v97, v208, v14
	v_pk_fma_f32 v[98:99], v[208:209], s[82:83], v[14:15] op_sel_hi:[1,1,0]
	v_pk_fma_f32 v[100:101], v[208:209], s[84:85], v[14:15] op_sel_hi:[1,1,0]
	v_pk_fma_f32 v[102:103], v[208:209], s[86:87], v[14:15] op_sel_hi:[1,1,0]
	v_pk_fma_f32 v[104:105], v[208:209], s[80:81], v[14:15] op_sel_hi:[1,1,0]
	v_pk_fma_f32 v[106:107], v[208:209], s[88:89], v[14:15] op_sel_hi:[1,1,0]
	v_pk_fma_f32 v[108:109], v[208:209], s[90:91], v[14:15] op_sel_hi:[1,1,0]
	v_pk_fma_f32 v[110:111], v[208:209], s[92:93], v[14:15] op_sel_hi:[1,1,0]
	v_add_f32_e32 v94, v166, v14
	v_fma_f32 v80, 0, v208, v94
	s_waitcnt lgkmcnt(3)
	v_mfma_f32_32x32x16_bf16 v[96:111], v[2:5], v[144:147], v[96:111]
	v_add_f32_e32 v81, v208, v94
	v_fma_f32 v82, v208, s82, v94
	v_fma_f32 v83, v209, s83, v94
	v_fma_f32 v84, v208, s84, v94
	v_fma_f32 v85, v209, s85, v94
	v_pk_fma_f32 v[86:87], v[208:209], s[86:87], v[94:95] op_sel_hi:[1,1,0]
	v_pk_fma_f32 v[88:89], v[208:209], s[80:81], v[94:95] op_sel_hi:[1,1,0]
	v_pk_fma_f32 v[90:91], v[208:209], s[88:89], v[94:95] op_sel_hi:[1,1,0]
	v_pk_fma_f32 v[92:93], v[208:209], s[90:91], v[94:95] op_sel_hi:[1,1,0]
	v_pk_fma_f32 v[94:95], v[208:209], s[92:93], v[94:95] op_sel_hi:[1,1,0]
	s_waitcnt lgkmcnt(2)
	v_mfma_f32_32x32x16_bf16 v[96:111], v[6:9], v[148:151], v[96:111]
	ds_read_b128 v[2:5], v128 offset:64
	ds_read_b128 v[6:9], v128 offset:96
	s_cmp_lg_u32 s10, s72
	s_waitcnt lgkmcnt(3)
	v_mfma_f32_32x32x16_bf16 v[80:95], v[10:13], v[144:147], v[80:95]
	s_waitcnt lgkmcnt(2)
	v_mfma_f32_32x32x16_bf16 v[80:95], v[124:127], v[148:151], v[80:95]
	s_waitcnt lgkmcnt(1)
	v_mfma_f32_32x32x16_bf16 v[96:111], v[2:5], v[152:155], v[96:111]
	ds_read_b128 v[2:5], v128 offset:4672
	ds_read_b128 v[174:177], v128 offset:4704
	s_waitcnt lgkmcnt(1)
	v_mfma_f32_32x32x16_bf16 v[80:95], v[2:5], v[152:155], v[80:95]
	v_add3_u32 v2, s12, v207, v244
	v_add_u32_e32 v3, 0x2000, v2
	v_add_u32_e32 v2, 0x3000, v2
	ds_read2_b64 v[140:143], v3 offset0:128 offset1:130
	ds_read2_b64 v[132:135], v3 offset0:132 offset1:134
	v_mfma_f32_32x32x16_bf16 v[96:111], v[6:9], v[156:159], v[96:111]
	ds_read2_b64 v[136:139], v2 offset0:160 offset1:162
	ds_read2_b64 v[128:131], v2 offset0:164 offset1:166
	ds_read2_b64 v[124:127], v3 offset0:136 offset1:138
	ds_read2_b64 v[10:13], v2 offset0:168 offset1:170
	ds_read2_b64 v[6:9], v3 offset0:140 offset1:142
	ds_read2_b64 v[2:5], v2 offset0:172 offset1:174
	s_waitcnt lgkmcnt(8)
	v_mfma_f32_32x32x16_bf16 v[80:95], v[174:177], v[156:159], v[80:95]
	s_cbranch_scc1 .LBB0_1001
	v_or_b32_e32 v14, 32, v1
	v_cmp_le_i32_e64 s[6:7], v14, v204
	v_or_b32_e32 v14, 33, v1
	v_cmp_le_i32_e64 s[8:9], v14, v204
	v_or_b32_e32 v14, 2, v1
	v_cmp_le_i32_e32 vcc, v1, v204
	s_nop 4
	v_cndmask_b32_e64 v81, v222, v81, s[8:9]
	v_cmp_le_i32_e64 s[8:9], v14, v204
	v_or_b32_e32 v14, 34, v1
	v_cmp_le_i32_e64 s[10:11], v14, v204
	v_or_b32_e32 v14, 3, v1
	v_cndmask_b32_e64 v80, v222, v80, s[6:7]
	v_cndmask_b32_e64 v82, v222, v82, s[10:11]
	v_cmp_le_i32_e64 s[10:11], v14, v204
	v_or_b32_e32 v14, 35, v1
	v_cmp_le_i32_e64 s[12:13], v14, v204
	v_or_b32_e32 v14, 8, v1
	v_cmp_lt_i32_e64 s[6:7], v1, v204
	v_cndmask_b32_e64 v83, v222, v83, s[12:13]
	v_cmp_le_i32_e64 s[12:13], v14, v204
	v_or_b32_e32 v14, 40, v1
	v_cmp_le_i32_e64 s[14:15], v14, v204
	v_or_b32_e32 v14, 9, v1
	s_nop 0
	v_cndmask_b32_e64 v84, v222, v84, s[14:15]
	v_cmp_le_i32_e64 s[14:15], v14, v204
	v_or_b32_e32 v14, 41, v1
	v_cmp_le_i32_e64 s[16:17], v14, v204
	v_or_b32_e32 v14, 10, v1
	s_nop 0
	v_cndmask_b32_e64 v85, v222, v85, s[16:17]
	v_cmp_le_i32_e64 s[16:17], v14, v204
	v_or_b32_e32 v14, 42, v1
	v_cmp_le_i32_e64 s[18:19], v14, v204
	v_or_b32_e32 v14, 11, v1
	s_nop 0
	v_cndmask_b32_e64 v86, v222, v86, s[18:19]
	v_cmp_le_i32_e64 s[18:19], v14, v204
	v_or_b32_e32 v14, 43, v1
	v_cmp_le_i32_e64 s[20:21], v14, v204
	v_or_b32_e32 v14, 16, v1
	s_nop 0
	v_cndmask_b32_e64 v87, v222, v87, s[20:21]
	v_cmp_le_i32_e64 s[20:21], v14, v204
	v_or_b32_e32 v14, 48, v1
	v_cmp_le_i32_e64 s[22:23], v14, v204
	v_or_b32_e32 v14, 17, v1
	s_nop 0
	v_cndmask_b32_e64 v88, v222, v88, s[22:23]
	v_cmp_le_i32_e64 s[22:23], v14, v204
	v_or_b32_e32 v14, 49, v1
	v_cmp_le_i32_e64 s[24:25], v14, v204
	v_or_b32_e32 v14, 18, v1
	s_nop 0
	v_cndmask_b32_e64 v89, v222, v89, s[24:25]
	v_cmp_le_i32_e64 s[24:25], v14, v204
	v_or_b32_e32 v14, 50, v1
	v_cmp_le_i32_e64 s[26:27], v14, v204
	v_or_b32_e32 v14, 19, v1
	s_nop 0
	v_cndmask_b32_e64 v90, v222, v90, s[26:27]
	v_cmp_le_i32_e64 s[26:27], v14, v204
	v_or_b32_e32 v14, 51, v1
	v_cmp_le_i32_e64 s[28:29], v14, v204
	v_or_b32_e32 v14, 24, v1
	s_nop 0
	v_cndmask_b32_e64 v91, v222, v91, s[28:29]
	v_cmp_le_i32_e64 s[28:29], v14, v204
	v_or_b32_e32 v14, 56, v1
	v_cmp_le_i32_e64 s[30:31], v14, v204
	v_or_b32_e32 v14, 25, v1
	s_nop 0
	v_cndmask_b32_e64 v92, v222, v92, s[30:31]
	v_cmp_le_i32_e64 s[30:31], v14, v204
	v_or_b32_e32 v14, 57, v1
	v_cmp_le_i32_e64 s[34:35], v14, v204
	v_or_b32_e32 v14, 26, v1
	s_nop 0
	v_cndmask_b32_e64 v93, v222, v93, s[34:35]
	v_cmp_le_i32_e64 s[34:35], v14, v204
	v_or_b32_e32 v14, 58, v1
	v_cmp_le_i32_e64 s[36:37], v14, v204
	v_or_b32_e32 v14, 27, v1
	v_or_b32_e32 v1, 59, v1
	v_cndmask_b32_e64 v94, v222, v94, s[36:37]
	v_cmp_le_i32_e64 s[36:37], v14, v204
	v_cmp_gt_i32_e64 s[38:39], v1, v204
	s_and_saveexec_b64 s[44:45], s[38:39]
	v_mov_b32_e32 v95, s75
	s_or_b64 exec, exec, s[44:45]
	v_cndmask_b32_e64 v97, v222, v97, s[6:7]
	v_cndmask_b32_e32 v96, v222, v96, vcc
	v_cndmask_b32_e64 v98, v222, v98, s[8:9]
	v_cndmask_b32_e64 v99, v222, v99, s[10:11]
	v_cndmask_b32_e64 v100, v222, v100, s[12:13]
	v_cndmask_b32_e64 v101, v222, v101, s[14:15]
	v_cndmask_b32_e64 v102, v222, v102, s[16:17]
	v_cndmask_b32_e64 v103, v222, v103, s[18:19]
	v_cndmask_b32_e64 v104, v222, v104, s[20:21]
	v_cndmask_b32_e64 v105, v222, v105, s[22:23]
	v_cndmask_b32_e64 v106, v222, v106, s[24:25]
	v_cndmask_b32_e64 v107, v222, v107, s[26:27]
	v_cndmask_b32_e64 v108, v222, v108, s[28:29]
	v_cndmask_b32_e64 v109, v222, v109, s[30:31]
	v_cndmask_b32_e64 v110, v222, v110, s[34:35]
	v_cndmask_b32_e64 v111, v222, v111, s[36:37]

; DI unsigned pk2(float lo, float hi) { f32x2 v = {lo, hi}; return __builtin_bit_cast(unsigned, __builtin_convertvector(v, bf2_t)); }
; DI float fast_exp2(float x) { return __builtin_amdgcn_exp2f(x); }
; #define MFMA32(a, b, c) __builtin_amdgcn_mfma_f32_32x32x16_bf16((a), (b), (c), 0, 0, 0)
; DI void pv_frag(const VFrag& V, const f32x16& p, f32x16& o0, f32x16& o1) {
; #pragma unroll
;     for (int s = 0; s < 2; ++s) {
;         u32x4 pw; pw.x = pk2(p[8 * s], p[8 * s + 1]); pw.y = pk2(p[8 * s + 2], p[8 * s + 3]); pw.z = pk2(p[8 * s + 4], p[8 * s + 5]); pw.w = pk2(p[8 * s + 6], p[8 * s + 7]);
;         const bf16x8 pf = __builtin_bit_cast(bf16x8, pw);
; #pragma unroll
;         for (int d0 = 0; d0 < 2; ++d0) {
;             const u32x2 lo = V.v[(2 * s + d0) * 2], h2 = V.v[(2 * s + d0) * 2 + 1];
;             u32x4 vw; vw.x = lo.x; vw.y = lo.y; vw.z = h2.x; vw.w = h2.y;
;             const bf16x8 vf = __builtin_bit_cast(bf16x8, vw);
;             if (d0 == 0) o0 = MFMA32(vf, pf, o0); else o1 = MFMA32(vf, pf, o1);
;         }
;     }
; }
; DI float soft_update(Soft& f, f32x16& x0, f32x16& x1, bool hasO) {
;     ...
;     f.seen = f.seen || valid;
;     float ls = 0.f;
; #pragma unroll
;     for (int r = 0; r < 16; ++r) { x0[r] = fast_exp2(x0[r]); x1[r] = fast_exp2(x1[r]); ls += x0[r] + x1[r]; }
;     f.l += ls;
.LBB0_1007:
	v_exp_f32_e32 v1, v96
	v_exp_f32_e32 v171, v80
	v_exp_f32_e32 v14, v97
	v_exp_f32_e32 v96, v81
	v_mov_b32_e32 v15, v0
	v_add_f32_e32 v97, v171, v1
	s_or_b64 s[4:5], s[4:5], s[6:7]
	v_pk_add_f32 v[80:81], v[96:97], v[14:15]
	v_exp_f32_e32 v15, v98
	v_pk_add_f32 v[174:175], v[80:81], v[80:81] op_sel_hi:[0,1]
	v_exp_f32_e32 v97, v82
	v_exp_f32_e32 v174, v99
	v_exp_f32_e32 v98, v83
	v_add_f32_e32 v99, v97, v15
	v_pk_add_f32 v[80:81], v[98:99], v[174:175]
	s_nop 0
	v_pk_add_f32 v[82:83], v[80:81], v[80:81] op_sel_hi:[0,1]
	v_exp_f32_e32 v99, v100
	v_exp_f32_e32 v175, v84
	v_exp_f32_e32 v82, v101
	v_exp_f32_e32 v84, v85
	v_add_f32_e32 v85, v175, v99
	v_pk_add_f32 v[80:81], v[84:85], v[82:83]
	s_nop 0
	v_pk_add_f32 v[100:101], v[80:81], v[80:81] op_sel_hi:[0,1]
	v_exp_f32_e32 v83, v102
	v_exp_f32_e32 v85, v86
	v_exp_f32_e32 v100, v103
	v_exp_f32_e32 v86, v87
	v_cvt_pk_bf16_f32 v82, v99, v82
	v_add_f32_e32 v87, v85, v83
	v_cvt_pk_bf16_f32 v83, v83, v100
	v_pk_add_f32 v[80:81], v[86:87], v[100:101]
	v_exp_f32_e32 v87, v104
	v_pk_add_f32 v[102:103], v[80:81], v[80:81] op_sel_hi:[0,1]
	v_exp_f32_e32 v101, v88
	v_exp_f32_e32 v102, v105
	v_exp_f32_e32 v88, v89
	v_add_f32_e32 v89, v101, v87
	v_pk_add_f32 v[80:81], v[88:89], v[102:103]
	s_nop 0
	v_pk_add_f32 v[104:105], v[80:81], v[80:81] op_sel_hi:[0,1]
	v_exp_f32_e32 v89, v106
	v_exp_f32_e32 v103, v90
	v_exp_f32_e32 v104, v107
	v_exp_f32_e32 v90, v91
	v_add_f32_e32 v91, v103, v89
	v_pk_add_f32 v[80:81], v[90:91], v[104:105]
	s_nop 0
	v_pk_add_f32 v[106:107], v[80:81], v[80:81] op_sel_hi:[0,1]
	v_exp_f32_e32 v91, v108
	v_cvt_pk_bf16_f32 v80, v1, v14
	v_exp_f32_e32 v1, v92
	v_exp_f32_e32 v106, v109
	v_exp_f32_e32 v14, v93
	v_cvt_pk_bf16_f32 v81, v15, v174
	v_add_f32_e32 v15, v1, v91
	v_pk_add_f32 v[92:93], v[14:15], v[106:107]
	s_andn2_b64 vcc, exec, s[42:43]
	s_cbranch_vccnz .Lsel_st_done
	s_xor_b32 s55, s2, 1
	s_mul_i32 s55, s55, 0x4600
	s_movk_i32 s56, 0x2400
	v_add_u32_e32 v179, s55, v243
	v_add3_u32 v184, s55, v241, v242
	v_add3_u32 v179, v179, v242, s56
	s_waitcnt vmcnt(1)
	ds_write_b128 v184, v[116:119]
	s_waitcnt vmcnt(0)
	ds_write2_b64 v179, v[120:121], v[122:123] offset1:1
.Lsel_st_done:
	s_waitcnt lgkmcnt(7)
	v_mfma_f32_32x32x16_bf16 v[64:79], v[140:143], v[80:83], v[64:79]
	v_pk_add_f32 v[92:93], v[92:93], v[92:93] op_sel_hi:[0,1]
	v_exp_f32_e32 v15, v110
	v_exp_f32_e32 v92, v111
	s_waitcnt lgkmcnt(5)
	v_mfma_f32_32x32x16_bf16 v[48:63], v[136:139], v[80:83], v[48:63]
	v_cvt_pk_bf16_f32 v80, v87, v102
	v_cvt_pk_bf16_f32 v81, v89, v104
	v_cvt_pk_bf16_f32 v82, v91, v106
	v_cvt_pk_bf16_f32 v83, v15, v92
	s_nop 1
	v_mfma_f32_32x32x16_bf16 v[64:79], v[132:135], v[80:83], v[64:79]
	s_waitcnt lgkmcnt(4)
	v_mfma_f32_32x32x16_bf16 v[48:63], v[128:131], v[80:83], v[48:63]
	v_cvt_pk_bf16_f32 v80, v171, v96
	v_cvt_pk_bf16_f32 v81, v97, v98
	v_cvt_pk_bf16_f32 v82, v175, v84
	v_cvt_pk_bf16_f32 v83, v85, v86
	s_waitcnt lgkmcnt(3)
	s_nop 0
	v_mfma_f32_32x32x16_bf16 v[64:79], v[124:127], v[80:83], v[64:79]
	s_waitcnt lgkmcnt(2)
	v_mfma_f32_32x32x16_bf16 v[48:63], v[10:13], v[80:83], v[48:63]
	v_exp_f32_e32 v81, v94
	v_exp_f32_e32 v80, v95
	v_cvt_pk_bf16_f32 v10, v101, v88
	v_cvt_pk_bf16_f32 v11, v103, v90
	v_cvt_pk_bf16_f32 v12, v1, v14
	v_cvt_pk_bf16_f32 v13, v81, v80
	v_add_f32_e32 v81, v81, v15
	s_waitcnt lgkmcnt(1)
	v_mfma_f32_32x32x16_bf16 v[64:79], v[6:9], v[10:13], v[64:79]
	v_add_f32_e64 v6, v80, v92
	v_add_f32_e64 v7, v81, v93
	v_add_f32_e32 v1, v6, v7
	v_add_f32_e32 v211, v211, v1
	s_waitcnt lgkmcnt(0)
	v_mfma_f32_32x32x16_bf16 v[48:63], v[2:5], v[10:13], v[48:63]
	s_xor_b32 s2, s2, 1
	s_branch .LBB0_1010
.LBB0_1008:
	s_andn2_b64 vcc, exec, s[42:43]
	s_xor_b32 s2, s2, 1
	s_cbranch_vccnz .LBB0_1010
	s_mul_i32 s6, s2, 0x4600
	s_add_i32 s6, s6, 0
	v_add_u32_e32 v179, s6, v243
	s_movk_i32 s7, 0x2400
	v_add3_u32 v184, s6, v241, v242
	v_add3_u32 v179, v179, v242, s7
	s_waitcnt vmcnt(1)
	ds_write_b128 v184, v[116:119]
	s_waitcnt vmcnt(0)
	ds_write2_b64 v179, v[120:121], v[122:123] offset1:1
